# attention: per-SIMD DMA issue stagger - waves 4-7 issue their LDS-DMA pieces at the tile head, waves 0-3 after the fifth QK MFMA
# speedup vs baseline: 1.0009x; 1.0009x over previous
.LBB0_877:
	s_or_b64 exec, exec, s[0:1]
	v_lshrrev_b32_e32 v244, 1, v254
	v_and_b32_e32 v244, 0x80, v244
	v_xor_b32_e32 v244, v244, v254
	v_mov_b32_e32 v1, v244
	s_waitcnt lgkmcnt(0)
	s_barrier
	s_cmp_lg_u32 0, -1
	v_lshrrev_b32_e32 v5, 2, v1
	v_lshrrev_b32_e32 v2, 5, v1
	v_lshlrev_b32_e32 v4, 2, v1
	v_and_b32_e32 v6, 2, v5
	v_and_or_b32 v4, v4, 12, v6
	v_xor_b32_e32 v6, v2, v5
	v_and_or_b32 v4, v6, 1, v4
	v_lshrrev_b32_e32 v6, 1, v1
	v_and_b32_e32 v0, 31, v1
	v_xor_b32_e32 v2, v2, v6
	v_lshlrev_b32_e32 v7, 7, v0
	v_lshlrev_b32_e32 v2, 4, v2
	v_lshlrev_b32_e32 v6, 3, v1
	v_bfe_u32 v3, v1, 5, 1
	v_and_or_b32 v2, v2, 16, v7
	v_and_b32_e32 v7, 0x60, v6
	v_bfe_u32 v8, v1, 2, 2
	v_and_b32_e32 v6, 8, v6
	s_cselect_b32 s0, 0, 0
	v_lshrrev_b32_e32 v9, 3, v1
	v_lshlrev_b32_e32 v12, 10, v3
	v_lshlrev_b32_e32 v13, 8, v8
	v_add_u32_e32 v6, s0, v6
	v_and_b32_e32 v10, 2, v9
	v_bfe_u32 v11, v1, 1, 1
	v_add3_u32 v6, v6, v12, v13
	v_or_b32_e32 v13, 2, v3
	v_lshlrev_b32_e32 v0, 8, v0
	v_bitop3_b32 v12, v10, v3, v11 bitop3:0x36
	v_bitop3_b32 v10, v10, v13, v11 bitop3:0x36
	v_lshl_or_b32 v198, v4, 4, v0
	v_lshlrev_b32_e32 v0, 4, v1
	v_lshlrev_b32_e32 v10, 4, v10
	s_movk_i32 s0, 0x800
	v_lshlrev_b32_e32 v8, 6, v8
	s_movk_i32 s16, 0x4000
	v_and_b32_e32 v0, 0x1f0, v0
	v_lshl_add_u32 v12, v12, 4, v6
	v_add3_u32 v6, v6, v10, s0
	v_xor_b32_e32 v10, 64, v8
	v_or3_b32 v199, v2, v7, s16
	v_lshl_or_b32 v2, v3, 9, v0
	v_mov_b32_e32 v0, 0
	v_add_u32_e32 v188, v12, v8
	v_add_u32_e32 v189, v6, v8
	v_add_u32_e32 v192, v12, v10
	v_add_u32_e32 v193, v6, v10
	v_xor_b32_e32 v10, 0x80, v8
	v_xor_b32_e32 v8, 0xc0, v8
	v_mov_b32_e32 v3, v0
	v_add_u32_e32 v196, v12, v8
	v_add_u32_e32 v197, v6, v8
	v_lshl_add_u64 v[162:163], s[36:37], 0, v[2:3]
	v_and_b32_e32 v2, 15, v1
	v_and_b32_e32 v5, 12, v5
	v_bfe_u32 v8, v1, 6, 2
	v_bitop3_b32 v2, v5, v2, v8 bitop3:0x36
	s_not_b32 s0, s2
	v_add_u32_e32 v3, 0x200, v1
	v_lshrrev_b32_e32 v4, 4, v1
	v_lshlrev_b32_e32 v2, 4, v2
	s_movk_i32 s7, 0x180
	s_add_i32 s17, s30, s0
	v_mad_u64_u32 v[164:165], s[0:1], v4, s7, v[2:3]
	v_bfe_u32 v7, v1, 4, 5
	v_lshrrev_b32_e32 v5, 4, v3
	s_mov_b32 s0, 0x1ffffe0
	v_add_u32_e32 v195, v6, v10
	s_movk_i32 s6, 0xc0
	v_ashrrev_i32_e32 v6, 6, v1
	v_ashrrev_i32_e32 v200, 8, v1
	v_and_or_b32 v5, v5, s0, v7
	v_xor_b32_e32 v1, v4, v1
	v_mad_u64_u32 v[166:167], s[0:1], v5, s7, v[2:3]
	v_mul_lo_u32 v5, v9, s6
	v_lshlrev_b32_e32 v1, 3, v1
	v_and_or_b32 v1, v1, 56, v5
	v_mov_b32_e32 v5, 0x100
	v_lshlrev_b32_e32 v4, 10, v6
	v_lshl_add_u32 v168, v1, 1, v5
	v_lshrrev_b32_e32 v1, 9, v3
	v_mul_u32_u24_e32 v1, 0x3000, v1
	v_mul_u32_u24_e32 v3, 0x180, v7
	v_add_u32_e32 v203, 0, v4
	s_mov_b32 s3, 0
	v_add_u32_e32 v194, v12, v10
	v_and_b32_e32 v201, 3, v6
	v_mov_b32_e32 v165, v0
	v_mov_b32_e32 v167, v0
	v_mov_b32_e32 v169, v0
	s_movk_i32 s36, 0x3000
	v_add3_u32 v170, v1, v3, v2
	s_movk_i32 s37, 0x1000
	s_movk_i32 s40, 0x2000
	v_add_u32_e32 v204, 0x2000, v203
	v_add_u32_e32 v205, 0x4000, v203
	s_mov_b64 s[0:1], 0x1dc06000
	s_mov_b32 s41, 0x8000
	s_mov_b64 s[6:7], 0x1dc0c000
	s_movk_i32 s44, 0xfe0
	s_movk_i32 s45, 0x2200
	s_mov_b32 s50, 0xc000
	s_mov_b32 s51, 0x10000
	s_mov_b32 s52, 0x14000
	s_mov_b32 s53, 0x18000
	v_mbcnt_hi_u32_b32 v191, -1, v186
	v_readfirstlane_b32 s74, v203
	v_readfirstlane_b32 s76, v244
	s_nop 0
	s_bfe_u32 s76, s76, 0x10007
	v_xor_b32_e32 v171, 0x20, v198
	v_xor_b32_e32 v174, 0x40, v198
	v_xor_b32_e32 v175, 0x60, v198
	v_xor_b32_e32 v176, 0x80, v198
	v_xor_b32_e32 v177, 0xa0, v198
	v_xor_b32_e32 v178, 0xc0, v198
	v_xor_b32_e32 v179, 0xe0, v198
	v_xor_b32_e32 v202, 0x20, v199
	v_xor_b32_e32 v207, 0x40, v199
	v_xor_b32_e32 v208, 0x60, v199
	v_mov_b32_e32 v1, 0x23ff8
	v_mov_b32_e32 v180, 0
	ds_write_b32 v1, v180
	s_mov_b32 s78, 0
	s_mov_b32 s54, 0
	v_readfirstlane_b32 s99, v254
	s_nop 3
	s_lshr_b32 s99, s99, 8
	s_xor_b32 s99, s99, 1
	s_branch .LBB0_879

.Lu884:
	s_add_u32 s72, s8, s0
	s_addc_u32 s73, s9, s1
	s_cmp_gt_u32 s57, s75
	s_cbranch_scc1 .LuA_skip
	s_cmp_lg_u32 s99, 0
	s_cbranch_scc1 .LuA_body
	s_add_u32 m0, s74, 0x6000
	s_nop 0
	global_load_lds_dwordx4 v164, s[72:73]
	s_add_u32 m0, s74, 0x8000
	s_nop 0
	global_load_lds_dwordx4 v170, s[72:73]
	s_add_u32 m0, s74, 0xa000
	s_nop 0
	global_load_lds_dwordx4 v168, s[72:73]
.LuA_body:
	ds_read_b128 v[146:149], v198
	ds_read_b128 v[150:153], v171
	ds_read_b128 v[246:249], v174
	ds_read_b128 v[250:253], v175
	ds_read_b128 v[180:183], v176
	ds_read_b128 v[184:187], v177
	s_waitcnt lgkmcnt(5)
	v_mfma_f32_32x32x16_bf16 v[82:97], v[146:149], v[98:101], v[210:225]
	ds_read_b128 v[146:149], v178
	s_waitcnt lgkmcnt(5)
	v_mfma_f32_32x32x16_bf16 v[82:97], v[150:153], v[102:105], v[82:97]
	ds_read_b128 v[150:153], v179
	s_waitcnt lgkmcnt(5)
	v_mfma_f32_32x32x16_bf16 v[82:97], v[246:249], v[106:109], v[82:97]
	ds_read_b128 v[246:249], v199
	s_waitcnt lgkmcnt(5)
	v_mfma_f32_32x32x16_bf16 v[82:97], v[250:253], v[110:113], v[82:97]
	ds_read_b128 v[250:253], v202
	s_waitcnt lgkmcnt(5)
	v_mfma_f32_32x32x16_bf16 v[82:97], v[180:183], v[122:125], v[82:97]
	ds_read_b128 v[180:183], v207
	s_cmp_lg_u32 s99, 0
	s_cbranch_scc0 .LuA_nolate
	s_add_u32 m0, s74, 0x6000
	s_nop 0
	global_load_lds_dwordx4 v164, s[72:73]
	s_add_u32 m0, s74, 0x8000
	s_nop 0
	global_load_lds_dwordx4 v170, s[72:73]
	s_add_u32 m0, s74, 0xa000
	s_nop 0
	global_load_lds_dwordx4 v168, s[72:73]
.LuA_nolate:
	s_waitcnt lgkmcnt(5)
	v_mfma_f32_32x32x16_bf16 v[82:97], v[184:187], v[114:117], v[82:97]
	ds_read_b128 v[184:187], v208
	s_waitcnt lgkmcnt(5)
	v_mfma_f32_32x32x16_bf16 v[82:97], v[146:149], v[118:121], v[82:97]
	ds_read_b128 v[146:149], v198 offset:8192
	s_waitcnt lgkmcnt(5)
	v_mfma_f32_32x32x16_bf16 v[82:97], v[150:153], v[126:129], v[82:97]
	ds_read_b128 v[150:153], v171 offset:8192
	s_waitcnt lgkmcnt(5)
	v_mfma_f32_32x32x16_bf16 v[82:97], v[246:249], v[130:133], v[82:97]
	ds_read_b128 v[246:249], v174 offset:8192
	s_waitcnt lgkmcnt(5)
	v_mfma_f32_32x32x16_bf16 v[82:97], v[250:253], v[134:137], v[82:97]
	ds_read_b128 v[250:253], v175 offset:8192
	s_waitcnt lgkmcnt(5)
	v_mfma_f32_32x32x16_bf16 v[82:97], v[180:183], v[138:141], v[82:97]
	ds_read_b128 v[180:183], v176 offset:8192
	s_waitcnt lgkmcnt(5)
	v_mfma_f32_32x32x16_bf16 v[82:97], v[184:187], v[142:145], v[82:97]
	ds_read_b128 v[184:187], v177 offset:8192
	ds_read_b64_tr_b16 v[238:239], v188 offset:0
	ds_read_b64_tr_b16 v[240:241], v189 offset:0
	s_waitcnt lgkmcnt(7)
	v_mfma_f32_32x32x16_bf16 v[66:81], v[146:149], v[98:101], v[210:225]
	ds_read_b128 v[146:149], v178 offset:8192
	ds_read_b64_tr_b16 v[234:235], v192 offset:0
	ds_read_b64_tr_b16 v[236:237], v193 offset:0
	s_waitcnt lgkmcnt(9)
	v_mfma_f32_32x32x16_bf16 v[66:81], v[150:153], v[102:105], v[66:81]
	ds_read_b128 v[150:153], v179 offset:8192
	ds_read_b64_tr_b16 v[230:231], v194 offset:0
	ds_read_b64_tr_b16 v[232:233], v195 offset:0
	v_exp_f32_e32 v82, v82
	v_exp_f32_e32 v83, v83
	v_exp_f32_e32 v84, v84
	v_add_f32_e32 v173, v173, v82
	s_waitcnt lgkmcnt(11)
	v_mfma_f32_32x32x16_bf16 v[66:81], v[246:249], v[106:109], v[66:81]
	ds_read_b128 v[246:249], v199 offset:4096
	ds_read_b64_tr_b16 v[226:227], v196 offset:0
	ds_read_b64_tr_b16 v[228:229], v197 offset:0
	v_exp_f32_e32 v85, v85
	v_mov_b32_e32 v242, v83
	v_cvt_pk_bf16_f32 v82, v82, v83
	v_exp_f32_e32 v86, v86
	s_waitcnt lgkmcnt(13)
	v_mfma_f32_32x32x16_bf16 v[66:81], v[250:253], v[110:113], v[66:81]
	ds_read_b128 v[250:253], v202 offset:4096
	v_add_f32_e32 v173, v173, v84
	v_exp_f32_e32 v87, v87
	v_add_f32_e32 v242, v242, v85
	v_cvt_pk_bf16_f32 v83, v84, v85
	s_waitcnt lgkmcnt(13)
	v_mfma_f32_32x32x16_bf16 v[66:81], v[180:183], v[122:125], v[66:81]
	ds_read_b128 v[180:183], v207 offset:4096
	v_exp_f32_e32 v88, v88
	v_add_f32_e32 v173, v173, v86
	v_exp_f32_e32 v89, v89
	v_add_f32_e32 v242, v242, v87
	s_waitcnt lgkmcnt(13)
	v_mfma_f32_32x32x16_bf16 v[66:81], v[184:187], v[114:117], v[66:81]
	ds_read_b128 v[184:187], v208 offset:4096
	v_cvt_pk_bf16_f32 v84, v86, v87
	v_add_f32_e32 v173, v173, v88
	v_add_f32_e32 v242, v242, v89
	v_cvt_pk_bf16_f32 v85, v88, v89
	s_waitcnt lgkmcnt(11)
	v_mfma_f32_32x32x16_bf16 v[66:81], v[146:149], v[118:121], v[66:81]
	v_exp_f32_e32 v90, v90
	v_exp_f32_e32 v91, v91
	v_exp_f32_e32 v92, v92
	v_add_f32_e32 v173, v173, v90
	s_waitcnt lgkmcnt(8)
	v_mfma_f32_32x32x16_bf16 v[66:81], v[150:153], v[126:129], v[66:81]
	v_exp_f32_e32 v93, v93
	v_add_f32_e32 v242, v242, v91
	v_cvt_pk_bf16_f32 v90, v90, v91
	v_exp_f32_e32 v94, v94
	s_waitcnt lgkmcnt(5)
	v_mfma_f32_32x32x16_bf16 v[66:81], v[246:249], v[130:133], v[66:81]
	v_add_f32_e32 v173, v173, v92
	v_exp_f32_e32 v95, v95
	v_add_f32_e32 v242, v242, v93
	s_waitcnt lgkmcnt(2)
	v_mfma_f32_32x32x16_bf16 v[66:81], v[250:253], v[134:137], v[66:81]
	v_cvt_pk_bf16_f32 v91, v92, v93
	v_exp_f32_e32 v96, v96
	v_add_f32_e32 v173, v173, v94
	s_waitcnt lgkmcnt(1)
	v_mfma_f32_32x32x16_bf16 v[66:81], v[180:183], v[138:141], v[66:81]
	v_exp_f32_e32 v97, v97
	v_add_f32_e32 v242, v242, v95
	v_cvt_pk_bf16_f32 v92, v94, v95
	s_waitcnt lgkmcnt(0)
	v_mfma_f32_32x32x16_bf16 v[66:81], v[184:187], v[142:145], v[66:81]
	v_add_f32_e32 v173, v173, v96
	v_add_f32_e32 v242, v242, v97
	v_cvt_pk_bf16_f32 v93, v96, v97
	ds_read_b64_tr_b16 v[158:159], v188 offset:0x1000
	ds_read_b64_tr_b16 v[160:161], v189 offset:0x1000
	ds_read_b64_tr_b16 v[154:155], v192 offset:0x1000
	ds_read_b64_tr_b16 v[156:157], v193 offset:0x1000
	ds_read_b64_tr_b16 v[150:151], v194 offset:0x1000
	ds_read_b64_tr_b16 v[152:153], v195 offset:0x1000
	ds_read_b64_tr_b16 v[146:147], v196 offset:0x1000
	ds_read_b64_tr_b16 v[148:149], v197 offset:0x1000
	v_mfma_f32_32x32x16_bf16 v[50:65], v[238:241], v[82:85], v[50:65]
	v_mfma_f32_32x32x16_bf16 v[34:49], v[234:237], v[82:85], v[34:49]
	v_exp_f32_e32 v66, v66
	v_exp_f32_e32 v67, v67
	v_exp_f32_e32 v68, v68
	v_add_f32_e32 v173, v173, v66
	v_mfma_f32_32x32x16_bf16 v[18:33], v[230:233], v[82:85], v[18:33]
	v_exp_f32_e32 v69, v69
	v_add_f32_e32 v242, v242, v67
	v_cvt_pk_bf16_f32 v66, v66, v67
	v_exp_f32_e32 v70, v70
	v_mfma_f32_32x32x16_bf16 v[2:17], v[226:229], v[82:85], v[2:17]
	v_add_f32_e32 v173, v173, v68
	v_exp_f32_e32 v71, v71
	v_add_f32_e32 v242, v242, v69
	ds_read_b64_tr_b16 v[238:239], v188 offset:0x2000
	ds_read_b64_tr_b16 v[240:241], v189 offset:0x2000
	ds_read_b64_tr_b16 v[234:235], v192 offset:0x2000
	ds_read_b64_tr_b16 v[236:237], v193 offset:0x2000
	ds_read_b64_tr_b16 v[230:231], v194 offset:0x2000
	ds_read_b64_tr_b16 v[232:233], v195 offset:0x2000
	ds_read_b64_tr_b16 v[226:227], v196 offset:0x2000
	ds_read_b64_tr_b16 v[228:229], v197 offset:0x2000
	s_waitcnt lgkmcnt(8)
	v_mfma_f32_32x32x16_bf16 v[50:65], v[158:161], v[90:93], v[50:65]
	v_cvt_pk_bf16_f32 v67, v68, v69
	v_exp_f32_e32 v72, v72
	v_add_f32_e32 v173, v173, v70
	v_exp_f32_e32 v73, v73
	v_mfma_f32_32x32x16_bf16 v[34:49], v[154:157], v[90:93], v[34:49]
	v_add_f32_e32 v242, v242, v71
	v_cvt_pk_bf16_f32 v68, v70, v71
	v_add_f32_e32 v173, v173, v72
	v_mfma_f32_32x32x16_bf16 v[18:33], v[150:153], v[90:93], v[18:33]
	v_add_f32_e32 v242, v242, v73
	v_cvt_pk_bf16_f32 v69, v72, v73
	v_exp_f32_e32 v74, v74
	v_mfma_f32_32x32x16_bf16 v[2:17], v[146:149], v[90:93], v[2:17]
	v_exp_f32_e32 v75, v75
	v_exp_f32_e32 v76, v76
	v_add_f32_e32 v173, v173, v74
	ds_read_b64_tr_b16 v[158:159], v188 offset:0x3000
	ds_read_b64_tr_b16 v[160:161], v189 offset:0x3000
	ds_read_b64_tr_b16 v[154:155], v192 offset:0x3000
	ds_read_b64_tr_b16 v[156:157], v193 offset:0x3000
	ds_read_b64_tr_b16 v[150:151], v194 offset:0x3000
	ds_read_b64_tr_b16 v[152:153], v195 offset:0x3000
	ds_read_b64_tr_b16 v[146:147], v196 offset:0x3000
	ds_read_b64_tr_b16 v[148:149], v197 offset:0x3000
	s_waitcnt lgkmcnt(8)
	v_mfma_f32_32x32x16_bf16 v[50:65], v[238:241], v[66:69], v[50:65]
	v_exp_f32_e32 v77, v77
	v_add_f32_e32 v242, v242, v75
	v_cvt_pk_bf16_f32 v74, v74, v75
	v_exp_f32_e32 v78, v78
	v_mfma_f32_32x32x16_bf16 v[34:49], v[234:237], v[66:69], v[34:49]
	v_add_f32_e32 v173, v173, v76
	v_exp_f32_e32 v79, v79
	v_add_f32_e32 v242, v242, v77
	v_cvt_pk_bf16_f32 v75, v76, v77
	v_mfma_f32_32x32x16_bf16 v[18:33], v[230:233], v[66:69], v[18:33]
	v_exp_f32_e32 v80, v80
	v_add_f32_e32 v173, v173, v78
	v_exp_f32_e32 v81, v81
	v_add_f32_e32 v242, v242, v79
	v_mfma_f32_32x32x16_bf16 v[2:17], v[226:229], v[66:69], v[2:17]
	v_cvt_pk_bf16_f32 v76, v78, v79
	v_add_f32_e32 v173, v173, v80
	v_add_f32_e32 v242, v242, v81
	v_cvt_pk_bf16_f32 v77, v80, v81
	s_waitcnt lgkmcnt(0)
	v_add_f32_e32 v173, v173, v242
	v_mfma_f32_32x32x16_bf16 v[50:65], v[158:161], v[74:77], v[50:65]
	v_mfma_f32_32x32x16_bf16 v[34:49], v[154:157], v[74:77], v[34:49]
	v_mfma_f32_32x32x16_bf16 v[18:33], v[150:153], v[74:77], v[18:33]
	v_mfma_f32_32x32x16_bf16 v[2:17], v[146:149], v[74:77], v[2:17]
.Lu888:
	s_cmp_ge_u32 s57, s56
	s_cselect_b64 s[12:13], -1, 0
	s_and_b64 vcc, exec, s[12:13]
	s_waitcnt vmcnt(0) lgkmcnt(0)
	s_barrier
	s_add_u32 s72, s8, s6
	s_addc_u32 s73, s9, s7
	s_cmp_ge_u32 s57, s75
	s_cbranch_scc1 .LuB_skip
	s_cmp_lg_u32 s99, 0
	s_cbranch_scc1 .LuB_body
	s_cbranch_vccnz .LuB_body
	s_mov_b32 m0, s74
	s_nop 0
	global_load_lds_dwordx4 v164, s[72:73]
	s_add_u32 m0, s74, 0x2000
	s_nop 0
	global_load_lds_dwordx4 v170, s[72:73]
	s_add_u32 m0, s74, 0x4000
	s_nop 0
	global_load_lds_dwordx4 v168, s[72:73]
.LuB_body:
	ds_read_b128 v[146:149], v198 offset:24576
	ds_read_b128 v[150:153], v171 offset:24576
	ds_read_b128 v[246:249], v174 offset:24576
	ds_read_b128 v[250:253], v175 offset:24576
	ds_read_b128 v[180:183], v176 offset:24576
	ds_read_b128 v[184:187], v177 offset:24576
	s_waitcnt lgkmcnt(5)
	v_mfma_f32_32x32x16_bf16 v[82:97], v[146:149], v[98:101], v[210:225]
	ds_read_b128 v[146:149], v178 offset:24576
	s_waitcnt lgkmcnt(5)
	v_mfma_f32_32x32x16_bf16 v[82:97], v[150:153], v[102:105], v[82:97]
	ds_read_b128 v[150:153], v179 offset:24576
	s_waitcnt lgkmcnt(5)
	v_mfma_f32_32x32x16_bf16 v[82:97], v[246:249], v[106:109], v[82:97]
	ds_read_b128 v[246:249], v199 offset:24576
	s_waitcnt lgkmcnt(5)
	v_mfma_f32_32x32x16_bf16 v[82:97], v[250:253], v[110:113], v[82:97]
	ds_read_b128 v[250:253], v202 offset:24576
	s_waitcnt lgkmcnt(5)
	v_mfma_f32_32x32x16_bf16 v[82:97], v[180:183], v[122:125], v[82:97]
	ds_read_b128 v[180:183], v207 offset:24576
	s_cmp_lg_u32 s99, 0
	s_cbranch_scc0 .LuB_nolate
	s_cbranch_vccnz .LuB_nolate
	s_mov_b32 m0, s74
	s_nop 0
	global_load_lds_dwordx4 v164, s[72:73]
	s_add_u32 m0, s74, 0x2000
	s_nop 0
	global_load_lds_dwordx4 v170, s[72:73]
	s_add_u32 m0, s74, 0x4000
	s_nop 0
	global_load_lds_dwordx4 v168, s[72:73]
.LuB_nolate:
	s_waitcnt lgkmcnt(5)
	v_mfma_f32_32x32x16_bf16 v[82:97], v[184:187], v[114:117], v[82:97]
	ds_read_b128 v[184:187], v208 offset:24576
	s_waitcnt lgkmcnt(5)
	v_mfma_f32_32x32x16_bf16 v[82:97], v[146:149], v[118:121], v[82:97]
	ds_read_b128 v[146:149], v198 offset:32768
	s_waitcnt lgkmcnt(5)
	v_mfma_f32_32x32x16_bf16 v[82:97], v[150:153], v[126:129], v[82:97]
	ds_read_b128 v[150:153], v171 offset:32768
	s_waitcnt lgkmcnt(5)
	v_mfma_f32_32x32x16_bf16 v[82:97], v[246:249], v[130:133], v[82:97]
	ds_read_b128 v[246:249], v174 offset:32768
	s_waitcnt lgkmcnt(5)
	v_mfma_f32_32x32x16_bf16 v[82:97], v[250:253], v[134:137], v[82:97]
	ds_read_b128 v[250:253], v175 offset:32768
	s_waitcnt lgkmcnt(5)
	v_mfma_f32_32x32x16_bf16 v[82:97], v[180:183], v[138:141], v[82:97]
	ds_read_b128 v[180:183], v176 offset:32768
	s_waitcnt lgkmcnt(5)
	v_mfma_f32_32x32x16_bf16 v[82:97], v[184:187], v[142:145], v[82:97]
	ds_read_b128 v[184:187], v177 offset:32768
	ds_read_b64_tr_b16 v[238:239], v188 offset:0x6000
	ds_read_b64_tr_b16 v[240:241], v189 offset:0x6000
	s_waitcnt lgkmcnt(7)
	v_mfma_f32_32x32x16_bf16 v[66:81], v[146:149], v[98:101], v[210:225]
	ds_read_b128 v[146:149], v178 offset:32768
	ds_read_b64_tr_b16 v[234:235], v192 offset:0x6000
	ds_read_b64_tr_b16 v[236:237], v193 offset:0x6000
	s_waitcnt lgkmcnt(9)
	v_mfma_f32_32x32x16_bf16 v[66:81], v[150:153], v[102:105], v[66:81]
	ds_read_b128 v[150:153], v179 offset:32768
	ds_read_b64_tr_b16 v[230:231], v194 offset:0x6000
	ds_read_b64_tr_b16 v[232:233], v195 offset:0x6000
	v_exp_f32_e32 v82, v82
	v_exp_f32_e32 v83, v83
	v_exp_f32_e32 v84, v84
	v_add_f32_e32 v173, v173, v82
	s_waitcnt lgkmcnt(11)
	v_mfma_f32_32x32x16_bf16 v[66:81], v[246:249], v[106:109], v[66:81]
	ds_read_b128 v[246:249], v199 offset:28672
	ds_read_b64_tr_b16 v[226:227], v196 offset:0x6000
	ds_read_b64_tr_b16 v[228:229], v197 offset:0x6000
	v_exp_f32_e32 v85, v85
	v_mov_b32_e32 v242, v83
	v_cvt_pk_bf16_f32 v82, v82, v83
	v_exp_f32_e32 v86, v86
	s_waitcnt lgkmcnt(13)
	v_mfma_f32_32x32x16_bf16 v[66:81], v[250:253], v[110:113], v[66:81]
	ds_read_b128 v[250:253], v202 offset:28672
	v_add_f32_e32 v173, v173, v84
	v_exp_f32_e32 v87, v87
	v_add_f32_e32 v242, v242, v85
	v_cvt_pk_bf16_f32 v83, v84, v85
	s_waitcnt lgkmcnt(13)
	v_mfma_f32_32x32x16_bf16 v[66:81], v[180:183], v[122:125], v[66:81]
	ds_read_b128 v[180:183], v207 offset:28672
	v_exp_f32_e32 v88, v88
	v_add_f32_e32 v173, v173, v86
	v_exp_f32_e32 v89, v89
	v_add_f32_e32 v242, v242, v87
	s_waitcnt lgkmcnt(13)
	v_mfma_f32_32x32x16_bf16 v[66:81], v[184:187], v[114:117], v[66:81]
	ds_read_b128 v[184:187], v208 offset:28672
	v_cvt_pk_bf16_f32 v84, v86, v87
	v_add_f32_e32 v173, v173, v88
	v_add_f32_e32 v242, v242, v89
	v_cvt_pk_bf16_f32 v85, v88, v89
	s_waitcnt lgkmcnt(11)
	v_mfma_f32_32x32x16_bf16 v[66:81], v[146:149], v[118:121], v[66:81]
	v_exp_f32_e32 v90, v90
	v_exp_f32_e32 v91, v91
	v_exp_f32_e32 v92, v92
	v_add_f32_e32 v173, v173, v90
	s_waitcnt lgkmcnt(8)
	v_mfma_f32_32x32x16_bf16 v[66:81], v[150:153], v[126:129], v[66:81]
	v_exp_f32_e32 v93, v93
	v_add_f32_e32 v242, v242, v91
	v_cvt_pk_bf16_f32 v90, v90, v91
	v_exp_f32_e32 v94, v94
	s_waitcnt lgkmcnt(5)
	v_mfma_f32_32x32x16_bf16 v[66:81], v[246:249], v[130:133], v[66:81]
	v_add_f32_e32 v173, v173, v92
	v_exp_f32_e32 v95, v95
	v_add_f32_e32 v242, v242, v93
	s_waitcnt lgkmcnt(2)
	v_mfma_f32_32x32x16_bf16 v[66:81], v[250:253], v[134:137], v[66:81]
	v_cvt_pk_bf16_f32 v91, v92, v93
	v_exp_f32_e32 v96, v96
	v_add_f32_e32 v173, v173, v94
	s_waitcnt lgkmcnt(1)
	v_mfma_f32_32x32x16_bf16 v[66:81], v[180:183], v[138:141], v[66:81]
	v_exp_f32_e32 v97, v97
	v_add_f32_e32 v242, v242, v95
	v_cvt_pk_bf16_f32 v92, v94, v95
	s_waitcnt lgkmcnt(0)
	v_mfma_f32_32x32x16_bf16 v[66:81], v[184:187], v[142:145], v[66:81]
	v_add_f32_e32 v173, v173, v96
	v_add_f32_e32 v242, v242, v97
	v_cvt_pk_bf16_f32 v93, v96, v97
	ds_read_b64_tr_b16 v[158:159], v188 offset:0x7000
	ds_read_b64_tr_b16 v[160:161], v189 offset:0x7000
	ds_read_b64_tr_b16 v[154:155], v192 offset:0x7000
	ds_read_b64_tr_b16 v[156:157], v193 offset:0x7000
	ds_read_b64_tr_b16 v[150:151], v194 offset:0x7000
	ds_read_b64_tr_b16 v[152:153], v195 offset:0x7000
	ds_read_b64_tr_b16 v[146:147], v196 offset:0x7000
	ds_read_b64_tr_b16 v[148:149], v197 offset:0x7000
	v_mfma_f32_32x32x16_bf16 v[50:65], v[238:241], v[82:85], v[50:65]
	v_mfma_f32_32x32x16_bf16 v[34:49], v[234:237], v[82:85], v[34:49]
	v_exp_f32_e32 v66, v66
	v_exp_f32_e32 v67, v67
	v_exp_f32_e32 v68, v68
	v_add_f32_e32 v173, v173, v66
	v_mfma_f32_32x32x16_bf16 v[18:33], v[230:233], v[82:85], v[18:33]
	v_exp_f32_e32 v69, v69
	v_add_f32_e32 v242, v242, v67
	v_cvt_pk_bf16_f32 v66, v66, v67
	v_exp_f32_e32 v70, v70
	v_mfma_f32_32x32x16_bf16 v[2:17], v[226:229], v[82:85], v[2:17]
	v_add_f32_e32 v173, v173, v68
	v_exp_f32_e32 v71, v71
	v_add_f32_e32 v242, v242, v69
	ds_read_b64_tr_b16 v[238:239], v188 offset:0x8000
	ds_read_b64_tr_b16 v[240:241], v189 offset:0x8000
	ds_read_b64_tr_b16 v[234:235], v192 offset:0x8000
	ds_read_b64_tr_b16 v[236:237], v193 offset:0x8000
	ds_read_b64_tr_b16 v[230:231], v194 offset:0x8000
	ds_read_b64_tr_b16 v[232:233], v195 offset:0x8000
	ds_read_b64_tr_b16 v[226:227], v196 offset:0x8000
	ds_read_b64_tr_b16 v[228:229], v197 offset:0x8000
	s_waitcnt lgkmcnt(8)
	v_mfma_f32_32x32x16_bf16 v[50:65], v[158:161], v[90:93], v[50:65]
	v_cvt_pk_bf16_f32 v67, v68, v69
	v_exp_f32_e32 v72, v72
	v_add_f32_e32 v173, v173, v70
	v_exp_f32_e32 v73, v73
	v_mfma_f32_32x32x16_bf16 v[34:49], v[154:157], v[90:93], v[34:49]
	v_add_f32_e32 v242, v242, v71
	v_cvt_pk_bf16_f32 v68, v70, v71
	v_add_f32_e32 v173, v173, v72
	v_mfma_f32_32x32x16_bf16 v[18:33], v[150:153], v[90:93], v[18:33]
	v_add_f32_e32 v242, v242, v73
	v_cvt_pk_bf16_f32 v69, v72, v73
	v_exp_f32_e32 v74, v74
	v_mfma_f32_32x32x16_bf16 v[2:17], v[146:149], v[90:93], v[2:17]
	v_exp_f32_e32 v75, v75
	v_exp_f32_e32 v76, v76
	v_add_f32_e32 v173, v173, v74
	ds_read_b64_tr_b16 v[158:159], v188 offset:0x9000
	ds_read_b64_tr_b16 v[160:161], v189 offset:0x9000
	ds_read_b64_tr_b16 v[154:155], v192 offset:0x9000
	ds_read_b64_tr_b16 v[156:157], v193 offset:0x9000
	ds_read_b64_tr_b16 v[150:151], v194 offset:0x9000
	ds_read_b64_tr_b16 v[152:153], v195 offset:0x9000
	ds_read_b64_tr_b16 v[146:147], v196 offset:0x9000
	ds_read_b64_tr_b16 v[148:149], v197 offset:0x9000
	s_waitcnt lgkmcnt(8)
	v_mfma_f32_32x32x16_bf16 v[50:65], v[238:241], v[66:69], v[50:65]
	v_exp_f32_e32 v77, v77
	v_add_f32_e32 v242, v242, v75
	v_cvt_pk_bf16_f32 v74, v74, v75
	v_exp_f32_e32 v78, v78
	v_mfma_f32_32x32x16_bf16 v[34:49], v[234:237], v[66:69], v[34:49]
	v_add_f32_e32 v173, v173, v76
	v_exp_f32_e32 v79, v79
	v_add_f32_e32 v242, v242, v77
	v_cvt_pk_bf16_f32 v75, v76, v77
	v_mfma_f32_32x32x16_bf16 v[18:33], v[230:233], v[66:69], v[18:33]
	v_exp_f32_e32 v80, v80
	v_add_f32_e32 v173, v173, v78
	v_exp_f32_e32 v81, v81
	v_add_f32_e32 v242, v242, v79
	v_mfma_f32_32x32x16_bf16 v[2:17], v[226:229], v[66:69], v[2:17]
	v_cvt_pk_bf16_f32 v76, v78, v79
	v_add_f32_e32 v173, v173, v80
	v_add_f32_e32 v242, v242, v81
	v_cvt_pk_bf16_f32 v77, v80, v81
	s_waitcnt lgkmcnt(0)
	v_add_f32_e32 v173, v173, v242
	v_mfma_f32_32x32x16_bf16 v[50:65], v[158:161], v[74:77], v[50:65]
	v_mfma_f32_32x32x16_bf16 v[34:49], v[154:157], v[74:77], v[34:49]
	v_mfma_f32_32x32x16_bf16 v[18:33], v[150:153], v[74:77], v[18:33]
	v_mfma_f32_32x32x16_bf16 v[2:17], v[146:149], v[74:77], v[2:17]
	s_branch .Lu883
.LuA_skip:
	s_add_u32 m0, s74, 0x6000
	s_nop 0
	global_load_lds_dwordx4 v164, s[72:73]
	s_add_u32 m0, s74, 0x8000
	s_nop 0
	global_load_lds_dwordx4 v170, s[72:73]
	s_add_u32 m0, s74, 0xa000
	s_nop 0
	global_load_lds_dwordx4 v168, s[72:73]
	s_branch .Lu888
.LuB_skip:
	s_cbranch_vccnz .Lu883
	s_mov_b32 m0, s74
	s_nop 0
	global_load_lds_dwordx4 v164, s[72:73]
	s_add_u32 m0, s74, 0x2000
	s_nop 0
	global_load_lds_dwordx4 v170, s[72:73]
	s_add_u32 m0, s74, 0x4000
	s_nop 0
	global_load_lds_dwordx4 v168, s[72:73]
	s_branch .Lu883
